# differential loop role A: QK MFMAs ordered score tile 0 first so its exponentials can start 4 states after the block instead of 12; row sums keep their order
# baseline (speedup 1.0000x reference)
; __device__ __forceinline__ s16x4 vtr(ldsp p) { return __builtin_bit_cast(s16x4, __builtin_amdgcn_ds_read_tr16_b64_v4i16((LAS v4i16_t*)p)); }
; template <bool DIFF>
; __device__ __forceinline__ void attn_unit(const AttnP& A, int b, int h, int qi, ldsp lds) {
;     ...
;             QK_BLOCK();
;             s16x4 vlo[8], vhi[8];
; #pragma unroll
;             for (int t = 0; t < 2; ++t)
; #pragma unroll
;                 for (int j = 0; j < 4; ++j) { vlo[t * 4 + j] = vtr(Vb + trb + (16 * j) * VP + t * 64); vhi[t * 4 + j] = vtr(Vb + trb + (16 * j + 8) * VP + t * 64); }
;             __builtin_amdgcn_sched_barrier(0);
;             MASK_BLOCK();
;             bool full = (kt == kt0);
;             float psa, psb;
;             if (!full) {
;                 EXPSUM_BLOCK();
;                 if (__any(psa + psb > 1.0e18f)) { full = true; QK_BLOCK();
;     ...
;             __builtin_amdgcn_s_setprio(1);
; #pragma unroll
;             for (int t = 0; t < 2; ++t)
; #pragma unroll
;                 for (int j = 0; j < 4; ++j) {
;                     const bf16x8 vf = (bf16x8){vlo[t * 4 + j][0], vlo[t * 4 + j][1], vlo[t * 4 + j][2], vlo[t * 4 + j][3], vhi[t * 4 + j][0], vhi[t * 4 + j][1], vhi[t * 4 + j][2], vhi[t * 4 + j][3]};
;                     o[t] = __builtin_amdgcn_mfma_f32_32x32x16_bf16(vf, pw[j], o[t], 0, 0, 0);
;                 }
;             if (DIFF) {
; #pragma unroll
;                 for (int t = 2; t < NTD; ++t)
; #pragma unroll
;                     for (int j = 0; j < 4; ++j) { vlo[(t - 2) * 4 + j] = vtr(Vb + trb + (16 * j) * VP + t * 64); vhi[(t - 2) * 4 + j] = vtr(Vb + trb + (16 * j + 8) * VP + t * 64); }
;                 __builtin_amdgcn_sched_barrier(0);
; #pragma unroll
;                 for (int t = 2; t < NTD; ++t)
; #pragma unroll
;                     for (int j = 0; j < 4; ++j) {
;                         const int i = (t - 2) * 4 + j;
;                         const bf16x8 vf = (bf16x8){vlo[i][0], vlo[i][1], vlo[i][2], vlo[i][3], vhi[i][0], vhi[i][1], vhi[i][2], vhi[i][3]};
;                         o[t] = __builtin_amdgcn_mfma_f32_32x32x16_bf16(vf, pw[j], o[t], 0, 0, 0);
;                     }
;             }
;             __builtin_amdgcn_s_setprio(0);
.Lda_s_even:
	ds_read_b64_tr_b16 v[148:149], v252 offset:17472
	ds_read_b64_tr_b16 v[150:151], v252 offset:20032
	ds_read_b64_tr_b16 v[152:153], v252 offset:17408
	ds_read_b64_tr_b16 v[154:155], v252 offset:19968
	ds_read_b64_tr_b16 v[156:157], v252 offset:22592
	ds_read_b64_tr_b16 v[158:159], v252 offset:25152
	ds_read_b64_tr_b16 v[160:161], v252 offset:22528
	ds_read_b64_tr_b16 v[162:163], v252 offset:25088
	ds_read_b64_tr_b16 v[164:165], v252 offset:27712
	ds_read_b64_tr_b16 v[166:167], v252 offset:30272
	ds_read_b64_tr_b16 v[168:169], v252 offset:27648
	ds_read_b64_tr_b16 v[170:171], v252 offset:30208
	ds_read_b64_tr_b16 v[172:173], v252 offset:32768
	ds_read_b64_tr_b16 v[174:175], v252 offset:35328
	ds_read_b64_tr_b16 v[176:177], v252 offset:32832
	ds_read_b64_tr_b16 v[178:179], v252 offset:35392
	s_waitcnt lgkmcnt(14)
	v_mfma_f32_32x32x16_bf16 v[34:49], v[148:151], v[98:101], v[34:49]
	ds_read_b64_tr_b16 v[90:91], v252 offset:17536
	ds_read_b64_tr_b16 v[92:93], v252 offset:20096
	s_waitcnt lgkmcnt(14)
	v_mfma_f32_32x32x16_bf16 v[50:65], v[152:155], v[98:101], v[50:65]
	ds_read_b64_tr_b16 v[94:95], v252 offset:17600
	ds_read_b64_tr_b16 v[96:97], v252 offset:20160
	s_waitcnt lgkmcnt(14)
	v_mfma_f32_32x32x16_bf16 v[34:49], v[156:159], v[102:105], v[34:49]
	ds_read_b64_tr_b16 v[106:107], v252 offset:22656
	ds_read_b64_tr_b16 v[108:109], v252 offset:25216
	s_waitcnt lgkmcnt(14)
	v_mfma_f32_32x32x16_bf16 v[50:65], v[160:163], v[102:105], v[50:65]
	ds_read_b64_tr_b16 v[110:111], v252 offset:22720
	ds_read_b64_tr_b16 v[112:113], v252 offset:25280
	s_waitcnt lgkmcnt(14)
	v_mfma_f32_32x32x16_bf16 v[34:49], v[164:167], v[82:85], v[34:49]
	ds_read_b64_tr_b16 v[240:241], v252 offset:27776
	ds_read_b64_tr_b16 v[242:243], v252 offset:30336
	s_waitcnt lgkmcnt(14)
	v_mfma_f32_32x32x16_bf16 v[50:65], v[168:171], v[82:85], v[50:65]
	ds_read_b64_tr_b16 v[148:149], v252 offset:27840
	ds_read_b64_tr_b16 v[150:151], v252 offset:30400
	s_waitcnt lgkmcnt(14)
	v_mfma_f32_32x32x16_bf16 v[50:65], v[172:175], v[86:89], v[50:65]
	ds_read_b64_tr_b16 v[152:153], v252 offset:32896
	ds_read_b64_tr_b16 v[154:155], v252 offset:35456
	s_waitcnt lgkmcnt(14)
	v_mfma_f32_32x32x16_bf16 v[34:49], v[176:179], v[86:89], v[34:49]
	ds_read_b64_tr_b16 v[156:157], v252 offset:32960
	ds_read_b64_tr_b16 v[158:159], v252 offset:35520
	s_waitcnt lgkmcnt(14)
	v_mfma_f32_32x32x16_bf16 v[18:33], v[90:93], v[98:101], v[18:33]
	ds_read_b128 v[160:163], v234
	s_waitcnt lgkmcnt(13)
	v_mfma_f32_32x32x16_bf16 v[2:17], v[94:97], v[98:101], v[2:17]
	ds_read_b128 v[164:167], v234 offset:32
	s_waitcnt lgkmcnt(12)
	v_mfma_f32_32x32x16_bf16 v[18:33], v[106:109], v[102:105], v[18:33]
	ds_read_b128 v[168:171], v234 offset:64
	s_waitcnt lgkmcnt(11)
	v_mfma_f32_32x32x16_bf16 v[2:17], v[110:113], v[102:105], v[2:17]
	ds_read_b128 v[172:175], v234 offset:96
	s_waitcnt lgkmcnt(10)
	v_mfma_f32_32x32x16_bf16 v[18:33], v[240:243], v[82:85], v[18:33]
	ds_read_b128 v[176:179], v234 offset:8704
	s_waitcnt lgkmcnt(9)
	v_mfma_f32_32x32x16_bf16 v[2:17], v[148:151], v[82:85], v[2:17]
	ds_read_b128 v[240:243], v234 offset:8736
	s_waitcnt lgkmcnt(8)
	v_mfma_f32_32x32x16_bf16 v[18:33], v[152:155], v[86:89], v[18:33]
	ds_read_b128 v[148:151], v234 offset:8768
	s_waitcnt lgkmcnt(7)
	v_mfma_f32_32x32x16_bf16 v[2:17], v[156:159], v[86:89], v[2:17]
	ds_read_b128 v[152:155], v234 offset:8800
	s_waitcnt lgkmcnt(7)
	v_mfma_f32_32x32x16_bf16 v[98:113], v[160:163], v[116:119], v[66:81]
	s_waitcnt lgkmcnt(6)
	v_mfma_f32_32x32x16_bf16 v[98:113], v[164:167], v[120:123], v[98:113]
	s_waitcnt lgkmcnt(5)
	v_mfma_f32_32x32x16_bf16 v[98:113], v[168:171], v[124:127], v[98:113]
	s_waitcnt lgkmcnt(4)
	v_mfma_f32_32x32x16_bf16 v[98:113], v[172:175], v[128:131], v[98:113]
	s_waitcnt lgkmcnt(3)
	v_mfma_f32_32x32x16_bf16 v[82:97], v[176:179], v[116:119], v[66:81]
	s_waitcnt lgkmcnt(2)
	v_mfma_f32_32x32x16_bf16 v[82:97], v[240:243], v[120:123], v[82:97]
	s_waitcnt lgkmcnt(1)
	v_mfma_f32_32x32x16_bf16 v[82:97], v[148:151], v[124:127], v[82:97]
	s_waitcnt lgkmcnt(0)
	v_mfma_f32_32x32x16_bf16 v[82:97], v[152:155], v[128:131], v[82:97]
	s_nop 3
	v_exp_f32_e32 v148, v98
	v_exp_f32_e32 v149, v99
	v_exp_f32_e32 v150, v100
	v_add_f32_e32 v237, 0, v148
	v_exp_f32_e32 v151, v101
	v_add_f32_e32 v237, v149, v237
	v_exp_f32_e32 v152, v102
	v_add_f32_e32 v237, v150, v237
	v_exp_f32_e32 v153, v103
	v_add_f32_e32 v237, v151, v237
	v_exp_f32_e32 v154, v104
	v_add_f32_e32 v237, v152, v237
	v_exp_f32_e32 v155, v105
	v_add_f32_e32 v237, v153, v237
	v_exp_f32_e32 v156, v106
	v_add_f32_e32 v237, v154, v237
	v_exp_f32_e32 v157, v107
	v_add_f32_e32 v237, v155, v237
	v_exp_f32_e32 v158, v108
	v_add_f32_e32 v237, v156, v237
	v_exp_f32_e32 v159, v109
	v_add_f32_e32 v237, v157, v237
	v_exp_f32_e32 v160, v110
	v_add_f32_e32 v237, v158, v237
	v_exp_f32_e32 v161, v111
	v_add_f32_e32 v237, v159, v237
	v_exp_f32_e32 v162, v112
	v_add_f32_e32 v237, v160, v237
	v_exp_f32_e32 v163, v113
	v_add_f32_e32 v237, v161, v237
	v_add_f32_e32 v237, v162, v237
	v_add_f32_e32 v237, v163, v237
	v_exp_f32_e32 v164, v82
	v_exp_f32_e32 v165, v83
	v_exp_f32_e32 v166, v84
	v_add_f32_e32 v238, 0, v164
	v_exp_f32_e32 v167, v85
	v_add_f32_e32 v238, v165, v238
	v_exp_f32_e32 v168, v86
	v_add_f32_e32 v238, v166, v238
	v_exp_f32_e32 v169, v87
	v_add_f32_e32 v238, v167, v238
	v_exp_f32_e32 v170, v88
	v_add_f32_e32 v238, v168, v238
	v_exp_f32_e32 v171, v89
	v_add_f32_e32 v238, v169, v238
	v_exp_f32_e32 v172, v90
	v_add_f32_e32 v238, v170, v238
	v_exp_f32_e32 v173, v91
	v_add_f32_e32 v238, v171, v238
	v_exp_f32_e32 v174, v92
	v_add_f32_e32 v238, v172, v238
	v_exp_f32_e32 v175, v93
	v_add_f32_e32 v238, v173, v238
	v_exp_f32_e32 v176, v94
	v_add_f32_e32 v238, v174, v238
	v_exp_f32_e32 v177, v95
	v_add_f32_e32 v238, v175, v238
	v_exp_f32_e32 v178, v96
	v_add_f32_e32 v238, v176, v238
	v_exp_f32_e32 v179, v97
	v_add_f32_e32 v238, v177, v238
	v_add_f32_e32 v238, v178, v238
	v_add_f32_e32 v238, v179, v238
	v_add_f32_e32 v204, v237, v238
	v_cmp_lt_f32_e32 vcc, s85, v204
	s_cbranch_vccnz .Lda_s_slow
; __device__ __forceinline__ unsigned cvtpk(float lo, float hi) { f32x2 v = {lo, hi}; bf16x2_t b = __builtin_convertvector(v, bf16x2_t); return __builtin_bit_cast(unsigned, b); }
; template <bool DIFF>
; __device__ __forceinline__ void attn_unit(const AttnP& A, int b, int h, int qi, ldsp lds) {
;     ...
;             l_run += psa + psb;
;     ...
;             bf16x8 pw[4];
; #pragma unroll
;             for (int j = 0; j < 4; ++j) {
;                 u32x4 pk;
;                 if (j < 2) { const int rb = 8 * (j & 1); pk.x = cvtpk(s0[rb], s0[rb + 1]); pk.y = cvtpk(s0[rb + 2], s0[rb + 3]); pk.z = cvtpk(s0[rb + 4], s0[rb + 5]); pk.w = cvtpk(s0[rb + 6], s0[rb + 7]); }
;                 else { const int rb = 8 * (j & 1); pk.x = cvtpk(s1[rb], s1[rb + 1]); pk.y = cvtpk(s1[rb + 2], s1[rb + 3]); pk.z = cvtpk(s1[rb + 4], s1[rb + 5]); pk.w = cvtpk(s1[rb + 6], s1[rb + 7]); }
;                 pw[j] = __builtin_bit_cast(bf16x8, pk);
;             }
;             __builtin_amdgcn_sched_barrier(0);
;             __builtin_amdgcn_s_setprio(1);
; #pragma unroll
;             for (int t = 0; t < 2; ++t)
; #pragma unroll
;                 for (int j = 0; j < 4; ++j) {
;                     const bf16x8 vf = (bf16x8){vlo[t * 4 + j][0], vlo[t * 4 + j][1], vlo[t * 4 + j][2], vlo[t * 4 + j][3], vhi[t * 4 + j][0], vhi[t * 4 + j][1], vhi[t * 4 + j][2], vhi[t * 4 + j][3]};
;                     o[t] = __builtin_amdgcn_mfma_f32_32x32x16_bf16(vf, pw[j], o[t], 0, 0, 0);
;                 }
;             if (DIFF) {
; #pragma unroll
;                 for (int t = 2; t < NTD; ++t)
; #pragma unroll
;                     for (int j = 0; j < 4; ++j) { vlo[(t - 2) * 4 + j] = vtr(Vb + trb + (16 * j) * VP + t * 64); vhi[(t - 2) * 4 + j] = vtr(Vb + trb + (16 * j + 8) * VP + t * 64); }
;                 __builtin_amdgcn_sched_barrier(0);
; #pragma unroll
;                 for (int t = 2; t < NTD; ++t)
; #pragma unroll
;                     for (int j = 0; j < 4; ++j) {
;                         const int i = (t - 2) * 4 + j;
;                         const bf16x8 vf = (bf16x8){vlo[i][0], vlo[i][1], vlo[i][2], vlo[i][3], vhi[i][0], vhi[i][1], vhi[i][2], vhi[i][3]};
;                         o[t] = __builtin_amdgcn_mfma_f32_32x32x16_bf16(vf, pw[j], o[t], 0, 0, 0);
;                     }
;             }
;             __builtin_amdgcn_s_setprio(0);
;         }
;         if (kt + 1 < nt) STORE_TILE((kt + 1) & 1);
	v_cvt_pk_bf16_f32 v98, v148, v149
	v_cvt_pk_bf16_f32 v99, v150, v151
	v_cvt_pk_bf16_f32 v100, v152, v153
	v_cvt_pk_bf16_f32 v101, v154, v155
	v_cvt_pk_bf16_f32 v102, v156, v157
	v_cvt_pk_bf16_f32 v103, v158, v159
	v_cvt_pk_bf16_f32 v104, v160, v161
	v_cvt_pk_bf16_f32 v105, v162, v163
	v_cvt_pk_bf16_f32 v82, v164, v165
	v_cvt_pk_bf16_f32 v83, v166, v167
	v_cvt_pk_bf16_f32 v84, v168, v169
	v_cvt_pk_bf16_f32 v85, v170, v171
	v_cvt_pk_bf16_f32 v86, v172, v173
	v_cvt_pk_bf16_f32 v87, v174, v175
	v_cvt_pk_bf16_f32 v88, v176, v177
	v_cvt_pk_bf16_f32 v89, v178, v179
	v_add_f32_e32 v230, v204, v230
	s_waitcnt vmcnt(0)
	ds_write_b128 v226, v[132:135] offset:38144
	ds_write_b128 v228, v[140:143] offset:38144
	ds_write_b128 v227, v[136:139] offset:17408
	ds_write_b128 v229, v[144:147] offset:17408
	global_load_dwordx4 v[136:139], v[196:197], off offset:2048
	global_load_dwordx4 v[144:147], v[198:199], off offset:2048
	v_lshl_add_u64 v[196:197], v[196:197], 0, s[26:27]
	v_lshl_add_u64 v[198:199], v[198:199], 0, s[26:27]
	global_load_dwordx4 v[132:135], v[196:197], off offset:1024
	global_load_dwordx4 v[140:143], v[198:199], off offset:1024
	s_waitcnt lgkmcnt(0)
	s_barrier
	s_add_i32 s75, s75, 1
	s_add_i32 s74, s74, 64
	s_cmp_gt_i32 s75, s23
	s_cbranch_scc1 .Lda_gen
.Lda_s_odd:
	ds_read_b64_tr_b16 v[148:149], v231 offset:17472
	ds_read_b64_tr_b16 v[150:151], v231 offset:20032
	ds_read_b64_tr_b16 v[152:153], v231 offset:17408
	ds_read_b64_tr_b16 v[154:155], v231 offset:19968
	ds_read_b64_tr_b16 v[156:157], v231 offset:22592
	ds_read_b64_tr_b16 v[158:159], v231 offset:25152
	ds_read_b64_tr_b16 v[160:161], v231 offset:22528
	ds_read_b64_tr_b16 v[162:163], v231 offset:25088
	ds_read_b64_tr_b16 v[164:165], v231 offset:27712
	ds_read_b64_tr_b16 v[166:167], v231 offset:30272
	ds_read_b64_tr_b16 v[168:169], v231 offset:27648
	ds_read_b64_tr_b16 v[170:171], v231 offset:30208
	ds_read_b64_tr_b16 v[172:173], v231 offset:32768
	ds_read_b64_tr_b16 v[174:175], v231 offset:35328
	ds_read_b64_tr_b16 v[176:177], v231 offset:32832
	ds_read_b64_tr_b16 v[178:179], v231 offset:35392
	s_waitcnt lgkmcnt(14)
	v_mfma_f32_32x32x16_bf16 v[34:49], v[148:151], v[98:101], v[34:49]
	ds_read_b64_tr_b16 v[90:91], v231 offset:17536
	ds_read_b64_tr_b16 v[92:93], v231 offset:20096
	s_waitcnt lgkmcnt(14)
	v_mfma_f32_32x32x16_bf16 v[50:65], v[152:155], v[98:101], v[50:65]
	ds_read_b64_tr_b16 v[94:95], v231 offset:17600
	ds_read_b64_tr_b16 v[96:97], v231 offset:20160
	s_waitcnt lgkmcnt(14)
	v_mfma_f32_32x32x16_bf16 v[34:49], v[156:159], v[102:105], v[34:49]
	ds_read_b64_tr_b16 v[106:107], v231 offset:22656
	ds_read_b64_tr_b16 v[108:109], v231 offset:25216
	s_waitcnt lgkmcnt(14)
	v_mfma_f32_32x32x16_bf16 v[50:65], v[160:163], v[102:105], v[50:65]
	ds_read_b64_tr_b16 v[110:111], v231 offset:22720
	ds_read_b64_tr_b16 v[112:113], v231 offset:25280
	s_waitcnt lgkmcnt(14)
	v_mfma_f32_32x32x16_bf16 v[34:49], v[164:167], v[82:85], v[34:49]
	ds_read_b64_tr_b16 v[240:241], v231 offset:27776
	ds_read_b64_tr_b16 v[242:243], v231 offset:30336
	s_waitcnt lgkmcnt(14)
	v_mfma_f32_32x32x16_bf16 v[50:65], v[168:171], v[82:85], v[50:65]
	ds_read_b64_tr_b16 v[148:149], v231 offset:27840
	ds_read_b64_tr_b16 v[150:151], v231 offset:30400
	s_waitcnt lgkmcnt(14)
	v_mfma_f32_32x32x16_bf16 v[50:65], v[172:175], v[86:89], v[50:65]
	ds_read_b64_tr_b16 v[152:153], v231 offset:32896
	ds_read_b64_tr_b16 v[154:155], v231 offset:35456
	s_waitcnt lgkmcnt(14)
	v_mfma_f32_32x32x16_bf16 v[34:49], v[176:179], v[86:89], v[34:49]
	ds_read_b64_tr_b16 v[156:157], v231 offset:32960
	ds_read_b64_tr_b16 v[158:159], v231 offset:35520
	s_waitcnt lgkmcnt(14)
	v_mfma_f32_32x32x16_bf16 v[18:33], v[90:93], v[98:101], v[18:33]
	ds_read_b128 v[160:163], v234 offset:38144
	s_waitcnt lgkmcnt(13)
	v_mfma_f32_32x32x16_bf16 v[2:17], v[94:97], v[98:101], v[2:17]
	ds_read_b128 v[164:167], v234 offset:38176
	s_waitcnt lgkmcnt(12)
	v_mfma_f32_32x32x16_bf16 v[18:33], v[106:109], v[102:105], v[18:33]
	ds_read_b128 v[168:171], v234 offset:38208
	s_waitcnt lgkmcnt(11)
	v_mfma_f32_32x32x16_bf16 v[2:17], v[110:113], v[102:105], v[2:17]
	ds_read_b128 v[172:175], v234 offset:38240
	s_waitcnt lgkmcnt(10)
	v_mfma_f32_32x32x16_bf16 v[18:33], v[240:243], v[82:85], v[18:33]
	ds_read_b128 v[176:179], v234 offset:46848
	s_waitcnt lgkmcnt(9)
; __device__ __forceinline__ s16x4 vtr(ldsp p) { return __builtin_bit_cast(s16x4, __builtin_amdgcn_ds_read_tr16_b64_v4i16((LAS v4i16_t*)p)); }
; template <bool DIFF>
; __device__ __forceinline__ void attn_unit(const AttnP& A, int b, int h, int qi, ldsp lds) {
;     ...
;             QK_BLOCK();
;             s16x4 vlo[8], vhi[8];
; #pragma unroll
;             for (int t = 0; t < 2; ++t)
; #pragma unroll
;                 for (int j = 0; j < 4; ++j) { vlo[t * 4 + j] = vtr(Vb + trb + (16 * j) * VP + t * 64); vhi[t * 4 + j] = vtr(Vb + trb + (16 * j + 8) * VP + t * 64); }
;             __builtin_amdgcn_sched_barrier(0);
;             MASK_BLOCK();
;             bool full = (kt == kt0);
;             float psa, psb;
;             if (!full) {
;                 EXPSUM_BLOCK();
;                 if (__any(psa + psb > 1.0e18f)) { full = true; QK_BLOCK();
; #pragma unroll
;                     for (int t = 0; t < 2; ++t)
; #pragma unroll
;                         for (int j = 0; j < 4; ++j) { vlo[t * 4 + j] = vtr(Vb + trb + (16 * j) * VP + t * 64); vhi[t * 4 + j] = vtr(Vb + trb + (16 * j + 8) * VP + t * 64); }
;                     MASK_BLOCK(); }
;             }
;             if (full) {
;                 float ma = fmaxf(fmaxf(s0[0], s0[1]), s1[0]), mb = fmaxf(fmaxf(s0[2], s0[3]), s1[1]);
;                 ma = fmaxf(fmaxf(ma, s1[2]), s1[3]);
; #pragma unroll
;                 for (int r = 4; r < 16; r += 4) { ma = fmaxf(fmaxf(ma, s0[r]), s0[r + 1]); mb = fmaxf(fmaxf(mb, s0[r + 2]), s0[r + 3]); ma = fmaxf(fmaxf(ma, s1[r]), s1[r + 1]); mb = fmaxf(fmaxf(mb, s1[r + 2]), s1[r + 3]); }
;                 const float rm = swap32_max(fmaxf(ma, mb));
;                 const float dl = (kt == kt0) ? ((rm == -INFINITY) ? 0.f : rm) : fmaxf(rm, 0.f);
;                 mhat += dl;
; #pragma unroll
;                 for (int r = 0; r < 16; ++r) { s0[r] -= dl; s1[r] -= dl; negm[r] = -mhat; }
;                 const float f = (kt == kt0) ? 1.0f : __builtin_amdgcn_exp2f(-dl);
;                 l_run *= f;
; #pragma unroll
;                 for (int t = 0; t < NTD; ++t)
; #pragma unroll
;                     for (int r = 0; r < 16; ++r) o[t][r] *= f;
;                 EXPSUM_BLOCK();
;             }
;             l_run += psa + psb;
;     ...
;             bf16x8 pw[4];
; #pragma unroll
;             for (int j = 0; j < 4; ++j) {
;                 u32x4 pk;
	v_mfma_f32_32x32x16_bf16 v[2:17], v[148:151], v[82:85], v[2:17]
	ds_read_b128 v[240:243], v234 offset:46880
	s_waitcnt lgkmcnt(8)
	v_mfma_f32_32x32x16_bf16 v[18:33], v[152:155], v[86:89], v[18:33]
	ds_read_b128 v[148:151], v234 offset:46912
	s_waitcnt lgkmcnt(7)
	v_mfma_f32_32x32x16_bf16 v[2:17], v[156:159], v[86:89], v[2:17]
	ds_read_b128 v[152:155], v234 offset:46944
	s_waitcnt lgkmcnt(7)
	v_mfma_f32_32x32x16_bf16 v[98:113], v[160:163], v[116:119], v[66:81]
	s_waitcnt lgkmcnt(6)
	v_mfma_f32_32x32x16_bf16 v[98:113], v[164:167], v[120:123], v[98:113]
	s_waitcnt lgkmcnt(5)
	v_mfma_f32_32x32x16_bf16 v[98:113], v[168:171], v[124:127], v[98:113]
	s_waitcnt lgkmcnt(4)
	v_mfma_f32_32x32x16_bf16 v[98:113], v[172:175], v[128:131], v[98:113]
	s_waitcnt lgkmcnt(3)
	v_mfma_f32_32x32x16_bf16 v[82:97], v[176:179], v[116:119], v[66:81]
	s_waitcnt lgkmcnt(2)
	v_mfma_f32_32x32x16_bf16 v[82:97], v[240:243], v[120:123], v[82:97]
	s_waitcnt lgkmcnt(1)
	v_mfma_f32_32x32x16_bf16 v[82:97], v[148:151], v[124:127], v[82:97]
	s_waitcnt lgkmcnt(0)
	v_mfma_f32_32x32x16_bf16 v[82:97], v[152:155], v[128:131], v[82:97]
	s_nop 3
	v_exp_f32_e32 v148, v98
	v_exp_f32_e32 v149, v99
	v_exp_f32_e32 v150, v100
	v_add_f32_e32 v237, 0, v148
	v_exp_f32_e32 v151, v101
	v_add_f32_e32 v237, v149, v237
	v_exp_f32_e32 v152, v102
	v_add_f32_e32 v237, v150, v237
	v_exp_f32_e32 v153, v103
	v_add_f32_e32 v237, v151, v237
	v_exp_f32_e32 v154, v104
	v_add_f32_e32 v237, v152, v237
	v_exp_f32_e32 v155, v105
	v_add_f32_e32 v237, v153, v237
	v_exp_f32_e32 v156, v106
	v_add_f32_e32 v237, v154, v237
	v_exp_f32_e32 v157, v107
	v_add_f32_e32 v237, v155, v237
	v_exp_f32_e32 v158, v108
	v_add_f32_e32 v237, v156, v237
	v_exp_f32_e32 v159, v109
	v_add_f32_e32 v237, v157, v237
	v_exp_f32_e32 v160, v110
	v_add_f32_e32 v237, v158, v237
	v_exp_f32_e32 v161, v111
	v_add_f32_e32 v237, v159, v237
	v_exp_f32_e32 v162, v112
	v_add_f32_e32 v237, v160, v237
	v_exp_f32_e32 v163, v113
	v_add_f32_e32 v237, v161, v237
	v_add_f32_e32 v237, v162, v237
	v_add_f32_e32 v237, v163, v237
	v_exp_f32_e32 v164, v82
	v_exp_f32_e32 v165, v83
	v_exp_f32_e32 v166, v84
	v_add_f32_e32 v238, 0, v164
	v_exp_f32_e32 v167, v85
	v_add_f32_e32 v238, v165, v238
	v_exp_f32_e32 v168, v86
	v_add_f32_e32 v238, v166, v238
	v_exp_f32_e32 v169, v87
	v_add_f32_e32 v238, v167, v238
	v_exp_f32_e32 v170, v88
	v_add_f32_e32 v238, v168, v238
	v_exp_f32_e32 v171, v89
	v_add_f32_e32 v238, v169, v238
	v_exp_f32_e32 v172, v90
	v_add_f32_e32 v238, v170, v238
	v_exp_f32_e32 v173, v91
	v_add_f32_e32 v238, v171, v238
	v_exp_f32_e32 v174, v92
	v_add_f32_e32 v238, v172, v238
	v_exp_f32_e32 v175, v93
	v_add_f32_e32 v238, v173, v238
	v_exp_f32_e32 v176, v94
	v_add_f32_e32 v238, v174, v238
	v_exp_f32_e32 v177, v95
	v_add_f32_e32 v238, v175, v238
	v_exp_f32_e32 v178, v96
	v_add_f32_e32 v238, v176, v238
	v_exp_f32_e32 v179, v97
	v_add_f32_e32 v238, v177, v238
	v_add_f32_e32 v238, v178, v238
	v_add_f32_e32 v238, v179, v238
	v_add_f32_e32 v204, v237, v238
	v_cmp_lt_f32_e32 vcc, s85, v204
	s_cbranch_vccnz .Lda_s_slow
	v_cvt_pk_bf16_f32 v98, v148, v149
	v_cvt_pk_bf16_f32 v99, v150, v151
	v_cvt_pk_bf16_f32 v100, v152, v153
	v_cvt_pk_bf16_f32 v101, v154, v155
	v_cvt_pk_bf16_f32 v102, v156, v157
	v_cvt_pk_bf16_f32 v103, v158, v159
	v_cvt_pk_bf16_f32 v104, v160, v161
	v_cvt_pk_bf16_f32 v105, v162, v163
	v_cvt_pk_bf16_f32 v82, v164, v165
	v_cvt_pk_bf16_f32 v83, v166, v167
	v_cvt_pk_bf16_f32 v84, v168, v169
	v_cvt_pk_bf16_f32 v85, v170, v171
	v_cvt_pk_bf16_f32 v86, v172, v173
	v_cvt_pk_bf16_f32 v87, v174, v175
	v_cvt_pk_bf16_f32 v88, v176, v177
	v_cvt_pk_bf16_f32 v89, v178, v179
	v_add_f32_e32 v230, v204, v230
	s_waitcnt vmcnt(0)
	ds_write_b128 v226, v[132:135]
	ds_write_b128 v228, v[140:143]
	ds_write_b128 v227, v[136:139] offset:55552
	ds_write_b128 v229, v[144:147] offset:55552
	global_load_dwordx4 v[136:139], v[196:197], off offset:2048
	global_load_dwordx4 v[144:147], v[198:199], off offset:2048
	v_lshl_add_u64 v[196:197], v[196:197], 0, s[26:27]
	v_lshl_add_u64 v[198:199], v[198:199], 0, s[26:27]
	global_load_dwordx4 v[132:135], v[196:197], off offset:1024
	global_load_dwordx4 v[140:143], v[198:199], off offset:1024
	s_waitcnt lgkmcnt(0)
	s_barrier
	s_add_i32 s75, s75, 1
	s_add_i32 s74, s74, 64
	s_cmp_le_i32 s75, s23
	s_cbranch_scc1 .Lda_s_even
